# conv_tile: 8-token loop unrolled, wave reductions batched (6 hops x 16 values instead of 48 serialized hops)
# baseline (speedup 1.0000x reference)
; DEV float bflo(unsigned u) { return __uint_as_float(u << 16); }
; DEV float bfhi(unsigned u) { return __uint_as_float(u & 0xffff0000u); }
; DEV void conv_tile(const Params& p, int tile, char* smem) {
;     ...
; #pragma unroll 1
;   for (int i = 0; i < 8; i++) {
;     float a0 = bb.x, a1 = bb.y;
; #pragma unroll
;     for (int wi = 0; wi < 31; wi++) {
;       unsigned u = *(const unsigned*)(stg + (i + wi) * 512 + c);
;       a0 += bflo(u) * w0[wi]; a1 += bfhi(u) * w1[wi];
;     }
;     *(float2*)(ybuf + i * 512 + c) = make_float2(a0, a1);
;     float s1 = wave_sum(a0 + a1);
;     float s2 = wave_sum(a0 * a0 + a1 * a1);
.LBB0_791:
	ds_read2st64_b32 v[70:71], v83 offset1:4
	s_waitcnt lgkmcnt(1)
	ds_read2st64_b32 v[72:73], v83 offset0:8 offset1:12
	ds_read2st64_b32 v[86:87], v83 offset0:16 offset1:20
	ds_read2st64_b32 v[92:93], v83 offset0:24 offset1:28
	ds_read2st64_b32 v[94:95], v83 offset0:32 offset1:36
	s_waitcnt lgkmcnt(4)
	v_lshlrev_b32_e32 v84, 16, v70
	v_and_b32_e32 v85, 0xffff0000, v70
	v_lshlrev_b32_e32 v70, 16, v71
	v_and_b32_e32 v71, 0xffff0000, v71
	s_waitcnt vmcnt(0)
	v_pk_fma_f32 v[84:85], v[62:63], v[84:85], v[68:69]
	s_waitcnt lgkmcnt(3)
	v_lshlrev_b32_e32 v88, 16, v72
	v_and_b32_e32 v89, 0xffff0000, v72
	v_pk_fma_f32 v[70:71], v[64:65], v[70:71], v[84:85]
	v_lshlrev_b32_e32 v72, 16, v73
	v_and_b32_e32 v73, 0xffff0000, v73
	v_pk_fma_f32 v[70:71], v[52:53], v[88:89], v[70:71]
	s_waitcnt lgkmcnt(2)
	v_lshlrev_b32_e32 v90, 16, v86
	v_and_b32_e32 v91, 0xffff0000, v86
	v_pk_fma_f32 v[70:71], v[54:55], v[72:73], v[70:71]
	v_lshlrev_b32_e32 v86, 16, v87
	v_and_b32_e32 v87, 0xffff0000, v87
	v_pk_fma_f32 v[70:71], v[48:49], v[90:91], v[70:71]
	ds_read2st64_b32 v[72:73], v83 offset0:40 offset1:44
	s_waitcnt lgkmcnt(2)
	v_lshlrev_b32_e32 v96, 16, v92
	v_and_b32_e32 v97, 0xffff0000, v92
	v_pk_fma_f32 v[70:71], v[50:51], v[86:87], v[70:71]
	v_lshlrev_b32_e32 v92, 16, v93
	v_and_b32_e32 v93, 0xffff0000, v93
	v_pk_fma_f32 v[70:71], v[56:57], v[96:97], v[70:71]
	ds_read2st64_b32 v[88:89], v83 offset0:48 offset1:52
	s_waitcnt lgkmcnt(2)
	v_lshlrev_b32_e32 v98, 16, v94
	v_and_b32_e32 v99, 0xffff0000, v94
	v_pk_fma_f32 v[70:71], v[58:59], v[92:93], v[70:71]
	v_lshlrev_b32_e32 v84, 16, v95
	v_pk_fma_f32 v[70:71], v[66:67], v[98:99], v[70:71]
	v_and_b32_e32 v85, 0xffff0000, v95
	ds_read2st64_b32 v[90:91], v83 offset0:56 offset1:60
	s_waitcnt lgkmcnt(2)
	v_lshlrev_b32_e32 v86, 16, v72
	v_and_b32_e32 v87, 0xffff0000, v72
	v_pk_fma_f32 v[70:71], v[60:61], v[84:85], v[70:71]
	v_lshlrev_b32_e32 v72, 16, v73
	v_and_b32_e32 v73, 0xffff0000, v73
	ds_read2st64_b32 v[96:97], v83 offset0:64 offset1:68
	v_pk_fma_f32 v[70:71], v[4:5], v[86:87], v[70:71]
	s_waitcnt lgkmcnt(2)
	v_lshlrev_b32_e32 v92, 16, v88
	v_and_b32_e32 v93, 0xffff0000, v88
	v_pk_fma_f32 v[70:71], v[6:7], v[72:73], v[70:71]
	v_lshlrev_b32_e32 v88, 16, v89
	v_and_b32_e32 v89, 0xffff0000, v89
	ds_read2st64_b32 v[98:99], v83 offset0:72 offset1:76
	v_pk_fma_f32 v[70:71], v[8:9], v[92:93], v[70:71]
	s_waitcnt lgkmcnt(2)
	v_lshlrev_b32_e32 v94, 16, v90
	v_and_b32_e32 v95, 0xffff0000, v90
	v_pk_fma_f32 v[70:71], v[10:11], v[88:89], v[70:71]
	v_lshlrev_b32_e32 v90, 16, v91
	v_and_b32_e32 v91, 0xffff0000, v91
	v_pk_fma_f32 v[70:71], v[12:13], v[94:95], v[70:71]
	ds_read2st64_b32 v[72:73], v83 offset0:80 offset1:84
	s_waitcnt lgkmcnt(2)
	v_lshlrev_b32_e32 v100, 16, v96
	v_and_b32_e32 v101, 0xffff0000, v96
	v_pk_fma_f32 v[70:71], v[14:15], v[90:91], v[70:71]
	v_lshlrev_b32_e32 v96, 16, v97
	v_and_b32_e32 v97, 0xffff0000, v97
	v_pk_fma_f32 v[70:71], v[16:17], v[100:101], v[70:71]
	ds_read2st64_b32 v[84:85], v83 offset0:88 offset1:92
	s_waitcnt lgkmcnt(2)
	v_lshlrev_b32_e32 v102, 16, v98
	v_and_b32_e32 v103, 0xffff0000, v98
	v_pk_fma_f32 v[70:71], v[20:21], v[96:97], v[70:71]
	v_lshlrev_b32_e32 v98, 16, v99
	v_and_b32_e32 v99, 0xffff0000, v99
	v_pk_fma_f32 v[70:71], v[22:23], v[102:103], v[70:71]
	ds_read2st64_b32 v[90:91], v83 offset0:96 offset1:100
	v_pk_fma_f32 v[70:71], v[24:25], v[98:99], v[70:71]
	s_waitcnt lgkmcnt(2)
	v_lshlrev_b32_e32 v86, 16, v72
	v_and_b32_e32 v87, 0xffff0000, v72
	v_lshlrev_b32_e32 v72, 16, v73
	v_and_b32_e32 v73, 0xffff0000, v73
	ds_read2st64_b32 v[92:93], v83 offset0:104 offset1:108
	v_pk_fma_f32 v[70:71], v[26:27], v[86:87], v[70:71]
	s_waitcnt lgkmcnt(2)
	v_lshlrev_b32_e32 v88, 16, v84
	v_and_b32_e32 v89, 0xffff0000, v84
	v_pk_fma_f32 v[70:71], v[28:29], v[72:73], v[70:71]
	v_lshlrev_b32_e32 v84, 16, v85
	v_and_b32_e32 v85, 0xffff0000, v85
	ds_read2st64_b32 v[98:99], v83 offset0:112 offset1:116
	v_pk_fma_f32 v[70:71], v[30:31], v[88:89], v[70:71]
	s_waitcnt lgkmcnt(2)
	v_lshlrev_b32_e32 v94, 16, v90
	v_and_b32_e32 v95, 0xffff0000, v90
	v_pk_fma_f32 v[70:71], v[32:33], v[84:85], v[70:71]
	v_lshlrev_b32_e32 v90, 16, v91
	v_and_b32_e32 v91, 0xffff0000, v91
	ds_read_b32 v103, v83 offset:30720
	v_pk_fma_f32 v[70:71], v[34:35], v[94:95], v[70:71]
	s_waitcnt lgkmcnt(2)
	v_lshlrev_b32_e32 v96, 16, v92
	v_and_b32_e32 v97, 0xffff0000, v92
	v_pk_fma_f32 v[70:71], v[36:37], v[90:91], v[70:71]
	v_lshlrev_b32_e32 v92, 16, v93
	v_and_b32_e32 v93, 0xffff0000, v93
	v_pk_fma_f32 v[70:71], v[38:39], v[96:97], v[70:71]
	s_waitcnt lgkmcnt(1)
	v_lshlrev_b32_e32 v100, 16, v98
	v_and_b32_e32 v101, 0xffff0000, v98
	v_pk_fma_f32 v[70:71], v[40:41], v[92:93], v[70:71]
	v_lshlrev_b32_e32 v98, 16, v99
	v_and_b32_e32 v99, 0xffff0000, v99
	v_pk_fma_f32 v[70:71], v[42:43], v[100:101], v[70:71]
	s_waitcnt lgkmcnt(0)
	v_lshlrev_b32_e32 v102, 16, v103
	v_and_b32_e32 v103, 0xffff0000, v103
	v_pk_fma_f32 v[70:71], v[44:45], v[98:99], v[70:71]
	s_nop 0
	v_pk_fma_f32 v[70:71], v[46:47], v[102:103], v[70:71]
	ds_write_b64 v82, v[70:71]
	v_pk_mul_f32 v[72:73], v[70:71], v[70:71]
	v_mov_b32_e32 v84, v71
	v_mov_b32_e32 v85, v73
	v_mov_b32_e32 v71, v72
	v_pk_add_f32 v[104:105], v[84:85], v[70:71]
	ds_read2st64_b32 v[70:71], v83 offset0:4 offset1:8
	s_waitcnt lgkmcnt(1)
	ds_read2st64_b32 v[72:73], v83 offset0:12 offset1:16
	ds_read2st64_b32 v[86:87], v83 offset0:20 offset1:24
	ds_read2st64_b32 v[92:93], v83 offset0:28 offset1:32
	ds_read2st64_b32 v[94:95], v83 offset0:36 offset1:40
	s_waitcnt lgkmcnt(4)
	v_lshlrev_b32_e32 v84, 16, v70
	v_and_b32_e32 v85, 0xffff0000, v70
	v_lshlrev_b32_e32 v70, 16, v71
	v_and_b32_e32 v71, 0xffff0000, v71
	s_waitcnt vmcnt(0)
; DEV float bflo(unsigned u) { return __uint_as_float(u << 16); }
; DEV float bfhi(unsigned u) { return __uint_as_float(u & 0xffff0000u); }
; DEV void conv_tile(const Params& p, int tile, char* smem) {
;     ...
; #pragma unroll 1
;   for (int i = 0; i < 8; i++) {
;     float a0 = bb.x, a1 = bb.y;
; #pragma unroll
;     for (int wi = 0; wi < 31; wi++) {
;       unsigned u = *(const unsigned*)(stg + (i + wi) * 512 + c);
;       a0 += bflo(u) * w0[wi]; a1 += bfhi(u) * w1[wi];
;     }
;     *(float2*)(ybuf + i * 512 + c) = make_float2(a0, a1);
;     float s1 = wave_sum(a0 + a1);
;     float s2 = wave_sum(a0 * a0 + a1 * a1);
	v_pk_fma_f32 v[84:85], v[62:63], v[84:85], v[68:69]
	s_waitcnt lgkmcnt(3)
	v_lshlrev_b32_e32 v88, 16, v72
	v_and_b32_e32 v89, 0xffff0000, v72
	v_pk_fma_f32 v[70:71], v[64:65], v[70:71], v[84:85]
	v_lshlrev_b32_e32 v72, 16, v73
	v_and_b32_e32 v73, 0xffff0000, v73
	v_pk_fma_f32 v[70:71], v[52:53], v[88:89], v[70:71]
	s_waitcnt lgkmcnt(2)
	v_lshlrev_b32_e32 v90, 16, v86
	v_and_b32_e32 v91, 0xffff0000, v86
	v_pk_fma_f32 v[70:71], v[54:55], v[72:73], v[70:71]
	v_lshlrev_b32_e32 v86, 16, v87
	v_and_b32_e32 v87, 0xffff0000, v87
	v_pk_fma_f32 v[70:71], v[48:49], v[90:91], v[70:71]
	ds_read2st64_b32 v[72:73], v83 offset0:44 offset1:48
	s_waitcnt lgkmcnt(2)
	v_lshlrev_b32_e32 v96, 16, v92
	v_and_b32_e32 v97, 0xffff0000, v92
	v_pk_fma_f32 v[70:71], v[50:51], v[86:87], v[70:71]
	v_lshlrev_b32_e32 v92, 16, v93
	v_and_b32_e32 v93, 0xffff0000, v93
	v_pk_fma_f32 v[70:71], v[56:57], v[96:97], v[70:71]
	ds_read2st64_b32 v[88:89], v83 offset0:52 offset1:56
	s_waitcnt lgkmcnt(2)
	v_lshlrev_b32_e32 v98, 16, v94
	v_and_b32_e32 v99, 0xffff0000, v94
	v_pk_fma_f32 v[70:71], v[58:59], v[92:93], v[70:71]
	v_lshlrev_b32_e32 v84, 16, v95
	v_pk_fma_f32 v[70:71], v[66:67], v[98:99], v[70:71]
	v_and_b32_e32 v85, 0xffff0000, v95
	ds_read2st64_b32 v[90:91], v83 offset0:60 offset1:64
	s_waitcnt lgkmcnt(2)
	v_lshlrev_b32_e32 v86, 16, v72
	v_and_b32_e32 v87, 0xffff0000, v72
	v_pk_fma_f32 v[70:71], v[60:61], v[84:85], v[70:71]
	v_lshlrev_b32_e32 v72, 16, v73
	v_and_b32_e32 v73, 0xffff0000, v73
	ds_read2st64_b32 v[96:97], v83 offset0:68 offset1:72
	v_pk_fma_f32 v[70:71], v[4:5], v[86:87], v[70:71]
	s_waitcnt lgkmcnt(2)
	v_lshlrev_b32_e32 v92, 16, v88
	v_and_b32_e32 v93, 0xffff0000, v88
	v_pk_fma_f32 v[70:71], v[6:7], v[72:73], v[70:71]
	v_lshlrev_b32_e32 v88, 16, v89
	v_and_b32_e32 v89, 0xffff0000, v89
	ds_read2st64_b32 v[98:99], v83 offset0:76 offset1:80
	v_pk_fma_f32 v[70:71], v[8:9], v[92:93], v[70:71]
	s_waitcnt lgkmcnt(2)
	v_lshlrev_b32_e32 v94, 16, v90
	v_and_b32_e32 v95, 0xffff0000, v90
	v_pk_fma_f32 v[70:71], v[10:11], v[88:89], v[70:71]
	v_lshlrev_b32_e32 v90, 16, v91
	v_and_b32_e32 v91, 0xffff0000, v91
	v_pk_fma_f32 v[70:71], v[12:13], v[94:95], v[70:71]
	ds_read2st64_b32 v[72:73], v83 offset0:84 offset1:88
	s_waitcnt lgkmcnt(2)
	v_lshlrev_b32_e32 v100, 16, v96
	v_and_b32_e32 v101, 0xffff0000, v96
	v_pk_fma_f32 v[70:71], v[14:15], v[90:91], v[70:71]
	v_lshlrev_b32_e32 v96, 16, v97
	v_and_b32_e32 v97, 0xffff0000, v97
	v_pk_fma_f32 v[70:71], v[16:17], v[100:101], v[70:71]
	ds_read2st64_b32 v[84:85], v83 offset0:92 offset1:96
	s_waitcnt lgkmcnt(2)
	v_lshlrev_b32_e32 v102, 16, v98
	v_and_b32_e32 v103, 0xffff0000, v98
	v_pk_fma_f32 v[70:71], v[20:21], v[96:97], v[70:71]
	v_lshlrev_b32_e32 v98, 16, v99
	v_and_b32_e32 v99, 0xffff0000, v99
	v_pk_fma_f32 v[70:71], v[22:23], v[102:103], v[70:71]
	ds_read2st64_b32 v[90:91], v83 offset0:100 offset1:104
	v_pk_fma_f32 v[70:71], v[24:25], v[98:99], v[70:71]
	s_waitcnt lgkmcnt(2)
	v_lshlrev_b32_e32 v86, 16, v72
	v_and_b32_e32 v87, 0xffff0000, v72
	v_lshlrev_b32_e32 v72, 16, v73
	v_and_b32_e32 v73, 0xffff0000, v73
	ds_read2st64_b32 v[92:93], v83 offset0:108 offset1:112
	v_pk_fma_f32 v[70:71], v[26:27], v[86:87], v[70:71]
	s_waitcnt lgkmcnt(2)
	v_lshlrev_b32_e32 v88, 16, v84
	v_and_b32_e32 v89, 0xffff0000, v84
	v_pk_fma_f32 v[70:71], v[28:29], v[72:73], v[70:71]
	v_lshlrev_b32_e32 v84, 16, v85
	v_and_b32_e32 v85, 0xffff0000, v85
	ds_read2st64_b32 v[98:99], v83 offset0:116 offset1:120
	v_pk_fma_f32 v[70:71], v[30:31], v[88:89], v[70:71]
	s_waitcnt lgkmcnt(2)
	v_lshlrev_b32_e32 v94, 16, v90
	v_and_b32_e32 v95, 0xffff0000, v90
	v_pk_fma_f32 v[70:71], v[32:33], v[84:85], v[70:71]
	v_lshlrev_b32_e32 v90, 16, v91
	v_and_b32_e32 v91, 0xffff0000, v91
	ds_read_b32 v103, v83 offset:31744
	v_pk_fma_f32 v[70:71], v[34:35], v[94:95], v[70:71]
	s_waitcnt lgkmcnt(2)
	v_lshlrev_b32_e32 v96, 16, v92
	v_and_b32_e32 v97, 0xffff0000, v92
	v_pk_fma_f32 v[70:71], v[36:37], v[90:91], v[70:71]
	v_lshlrev_b32_e32 v92, 16, v93
	v_and_b32_e32 v93, 0xffff0000, v93
	v_pk_fma_f32 v[70:71], v[38:39], v[96:97], v[70:71]
	s_waitcnt lgkmcnt(1)
	v_lshlrev_b32_e32 v100, 16, v98
	v_and_b32_e32 v101, 0xffff0000, v98
	v_pk_fma_f32 v[70:71], v[40:41], v[92:93], v[70:71]
	v_lshlrev_b32_e32 v98, 16, v99
	v_and_b32_e32 v99, 0xffff0000, v99
	v_pk_fma_f32 v[70:71], v[42:43], v[100:101], v[70:71]
	s_waitcnt lgkmcnt(0)
	v_lshlrev_b32_e32 v102, 16, v103
	v_and_b32_e32 v103, 0xffff0000, v103
	v_pk_fma_f32 v[70:71], v[44:45], v[98:99], v[70:71]
	s_nop 0
	v_pk_fma_f32 v[70:71], v[46:47], v[102:103], v[70:71]
	ds_write_b64 v82, v[70:71] offset:2048
	v_pk_mul_f32 v[72:73], v[70:71], v[70:71]
	v_mov_b32_e32 v84, v71
	v_mov_b32_e32 v85, v73
	v_mov_b32_e32 v71, v72
	v_pk_add_f32 v[106:107], v[84:85], v[70:71]
	ds_read2st64_b32 v[70:71], v83 offset0:8 offset1:12
	s_waitcnt lgkmcnt(1)
	ds_read2st64_b32 v[72:73], v83 offset0:16 offset1:20
	ds_read2st64_b32 v[86:87], v83 offset0:24 offset1:28
	ds_read2st64_b32 v[92:93], v83 offset0:32 offset1:36
	ds_read2st64_b32 v[94:95], v83 offset0:40 offset1:44
	s_waitcnt lgkmcnt(4)
	v_lshlrev_b32_e32 v84, 16, v70
	v_and_b32_e32 v85, 0xffff0000, v70
	v_lshlrev_b32_e32 v70, 16, v71
	v_and_b32_e32 v71, 0xffff0000, v71
	s_waitcnt vmcnt(0)
	v_pk_fma_f32 v[84:85], v[62:63], v[84:85], v[68:69]
	s_waitcnt lgkmcnt(3)
	v_lshlrev_b32_e32 v88, 16, v72
	v_and_b32_e32 v89, 0xffff0000, v72
	v_pk_fma_f32 v[70:71], v[64:65], v[70:71], v[84:85]
	v_lshlrev_b32_e32 v72, 16, v73
	v_and_b32_e32 v73, 0xffff0000, v73
	v_pk_fma_f32 v[70:71], v[52:53], v[88:89], v[70:71]
	s_waitcnt lgkmcnt(2)
; DEV float bflo(unsigned u) { return __uint_as_float(u << 16); }
; DEV float bfhi(unsigned u) { return __uint_as_float(u & 0xffff0000u); }
; DEV void conv_tile(const Params& p, int tile, char* smem) {
;     ...
; #pragma unroll 1
;   for (int i = 0; i < 8; i++) {
;     float a0 = bb.x, a1 = bb.y;
; #pragma unroll
;     for (int wi = 0; wi < 31; wi++) {
;       unsigned u = *(const unsigned*)(stg + (i + wi) * 512 + c);
;       a0 += bflo(u) * w0[wi]; a1 += bfhi(u) * w1[wi];
;     }
;     *(float2*)(ybuf + i * 512 + c) = make_float2(a0, a1);
;     float s1 = wave_sum(a0 + a1);
;     float s2 = wave_sum(a0 * a0 + a1 * a1);
	v_lshlrev_b32_e32 v90, 16, v86
	v_and_b32_e32 v91, 0xffff0000, v86
	v_pk_fma_f32 v[70:71], v[54:55], v[72:73], v[70:71]
	v_lshlrev_b32_e32 v86, 16, v87
	v_and_b32_e32 v87, 0xffff0000, v87
	v_pk_fma_f32 v[70:71], v[48:49], v[90:91], v[70:71]
	ds_read2st64_b32 v[72:73], v83 offset0:48 offset1:52
	s_waitcnt lgkmcnt(2)
	v_lshlrev_b32_e32 v96, 16, v92
	v_and_b32_e32 v97, 0xffff0000, v92
	v_pk_fma_f32 v[70:71], v[50:51], v[86:87], v[70:71]
	v_lshlrev_b32_e32 v92, 16, v93
	v_and_b32_e32 v93, 0xffff0000, v93
	v_pk_fma_f32 v[70:71], v[56:57], v[96:97], v[70:71]
	ds_read2st64_b32 v[88:89], v83 offset0:56 offset1:60
	s_waitcnt lgkmcnt(2)
	v_lshlrev_b32_e32 v98, 16, v94
	v_and_b32_e32 v99, 0xffff0000, v94
	v_pk_fma_f32 v[70:71], v[58:59], v[92:93], v[70:71]
	v_lshlrev_b32_e32 v84, 16, v95
	v_pk_fma_f32 v[70:71], v[66:67], v[98:99], v[70:71]
	v_and_b32_e32 v85, 0xffff0000, v95
	ds_read2st64_b32 v[90:91], v83 offset0:64 offset1:68
	s_waitcnt lgkmcnt(2)
	v_lshlrev_b32_e32 v86, 16, v72
	v_and_b32_e32 v87, 0xffff0000, v72
	v_pk_fma_f32 v[70:71], v[60:61], v[84:85], v[70:71]
	v_lshlrev_b32_e32 v72, 16, v73
	v_and_b32_e32 v73, 0xffff0000, v73
	ds_read2st64_b32 v[96:97], v83 offset0:72 offset1:76
	v_pk_fma_f32 v[70:71], v[4:5], v[86:87], v[70:71]
	s_waitcnt lgkmcnt(2)
	v_lshlrev_b32_e32 v92, 16, v88
	v_and_b32_e32 v93, 0xffff0000, v88
	v_pk_fma_f32 v[70:71], v[6:7], v[72:73], v[70:71]
	v_lshlrev_b32_e32 v88, 16, v89
	v_and_b32_e32 v89, 0xffff0000, v89
	ds_read2st64_b32 v[98:99], v83 offset0:80 offset1:84
	v_pk_fma_f32 v[70:71], v[8:9], v[92:93], v[70:71]
	s_waitcnt lgkmcnt(2)
	v_lshlrev_b32_e32 v94, 16, v90
	v_and_b32_e32 v95, 0xffff0000, v90
	v_pk_fma_f32 v[70:71], v[10:11], v[88:89], v[70:71]
	v_lshlrev_b32_e32 v90, 16, v91
	v_and_b32_e32 v91, 0xffff0000, v91
	v_pk_fma_f32 v[70:71], v[12:13], v[94:95], v[70:71]
	ds_read2st64_b32 v[72:73], v83 offset0:88 offset1:92
	s_waitcnt lgkmcnt(2)
	v_lshlrev_b32_e32 v100, 16, v96
	v_and_b32_e32 v101, 0xffff0000, v96
	v_pk_fma_f32 v[70:71], v[14:15], v[90:91], v[70:71]
	v_lshlrev_b32_e32 v96, 16, v97
	v_and_b32_e32 v97, 0xffff0000, v97
	v_pk_fma_f32 v[70:71], v[16:17], v[100:101], v[70:71]
	ds_read2st64_b32 v[84:85], v83 offset0:96 offset1:100
	s_waitcnt lgkmcnt(2)
	v_lshlrev_b32_e32 v102, 16, v98
	v_and_b32_e32 v103, 0xffff0000, v98
	v_pk_fma_f32 v[70:71], v[20:21], v[96:97], v[70:71]
	v_lshlrev_b32_e32 v98, 16, v99
	v_and_b32_e32 v99, 0xffff0000, v99
	v_pk_fma_f32 v[70:71], v[22:23], v[102:103], v[70:71]
	ds_read2st64_b32 v[90:91], v83 offset0:104 offset1:108
	v_pk_fma_f32 v[70:71], v[24:25], v[98:99], v[70:71]
	s_waitcnt lgkmcnt(2)
	v_lshlrev_b32_e32 v86, 16, v72
	v_and_b32_e32 v87, 0xffff0000, v72
	v_lshlrev_b32_e32 v72, 16, v73
	v_and_b32_e32 v73, 0xffff0000, v73
	ds_read2st64_b32 v[92:93], v83 offset0:112 offset1:116
	v_pk_fma_f32 v[70:71], v[26:27], v[86:87], v[70:71]
	s_waitcnt lgkmcnt(2)
	v_lshlrev_b32_e32 v88, 16, v84
	v_and_b32_e32 v89, 0xffff0000, v84
	v_pk_fma_f32 v[70:71], v[28:29], v[72:73], v[70:71]
	v_lshlrev_b32_e32 v84, 16, v85
	v_and_b32_e32 v85, 0xffff0000, v85
	ds_read2st64_b32 v[98:99], v83 offset0:120 offset1:124
	v_pk_fma_f32 v[70:71], v[30:31], v[88:89], v[70:71]
	s_waitcnt lgkmcnt(2)
	v_lshlrev_b32_e32 v94, 16, v90
	v_and_b32_e32 v95, 0xffff0000, v90
	v_pk_fma_f32 v[70:71], v[32:33], v[84:85], v[70:71]
	v_lshlrev_b32_e32 v90, 16, v91
	v_and_b32_e32 v91, 0xffff0000, v91
	ds_read_b32 v103, v83 offset:32768
	v_pk_fma_f32 v[70:71], v[34:35], v[94:95], v[70:71]
	s_waitcnt lgkmcnt(2)
	v_lshlrev_b32_e32 v96, 16, v92
	v_and_b32_e32 v97, 0xffff0000, v92
	v_pk_fma_f32 v[70:71], v[36:37], v[90:91], v[70:71]
	v_lshlrev_b32_e32 v92, 16, v93
	v_and_b32_e32 v93, 0xffff0000, v93
	v_pk_fma_f32 v[70:71], v[38:39], v[96:97], v[70:71]
	s_waitcnt lgkmcnt(1)
	v_lshlrev_b32_e32 v100, 16, v98
	v_and_b32_e32 v101, 0xffff0000, v98
	v_pk_fma_f32 v[70:71], v[40:41], v[92:93], v[70:71]
	v_lshlrev_b32_e32 v98, 16, v99
	v_and_b32_e32 v99, 0xffff0000, v99
	v_pk_fma_f32 v[70:71], v[42:43], v[100:101], v[70:71]
	s_waitcnt lgkmcnt(0)
	v_lshlrev_b32_e32 v102, 16, v103
	v_and_b32_e32 v103, 0xffff0000, v103
	v_pk_fma_f32 v[70:71], v[44:45], v[98:99], v[70:71]
	s_nop 0
	v_pk_fma_f32 v[70:71], v[46:47], v[102:103], v[70:71]
	ds_write_b64 v82, v[70:71] offset:4096
	v_pk_mul_f32 v[72:73], v[70:71], v[70:71]
	v_mov_b32_e32 v84, v71
	v_mov_b32_e32 v85, v73
	v_mov_b32_e32 v71, v72
	v_pk_add_f32 v[108:109], v[84:85], v[70:71]
	ds_read2st64_b32 v[70:71], v83 offset0:12 offset1:16
	s_waitcnt lgkmcnt(1)
	ds_read2st64_b32 v[72:73], v83 offset0:20 offset1:24
	ds_read2st64_b32 v[86:87], v83 offset0:28 offset1:32
	ds_read2st64_b32 v[92:93], v83 offset0:36 offset1:40
	ds_read2st64_b32 v[94:95], v83 offset0:44 offset1:48
	s_waitcnt lgkmcnt(4)
	v_lshlrev_b32_e32 v84, 16, v70
	v_and_b32_e32 v85, 0xffff0000, v70
	v_lshlrev_b32_e32 v70, 16, v71
	v_and_b32_e32 v71, 0xffff0000, v71
	s_waitcnt vmcnt(0)
	v_pk_fma_f32 v[84:85], v[62:63], v[84:85], v[68:69]
	s_waitcnt lgkmcnt(3)
	v_lshlrev_b32_e32 v88, 16, v72
	v_and_b32_e32 v89, 0xffff0000, v72
	v_pk_fma_f32 v[70:71], v[64:65], v[70:71], v[84:85]
	v_lshlrev_b32_e32 v72, 16, v73
	v_and_b32_e32 v73, 0xffff0000, v73
	v_pk_fma_f32 v[70:71], v[52:53], v[88:89], v[70:71]
	s_waitcnt lgkmcnt(2)
	v_lshlrev_b32_e32 v90, 16, v86
	v_and_b32_e32 v91, 0xffff0000, v86
	v_pk_fma_f32 v[70:71], v[54:55], v[72:73], v[70:71]
	v_lshlrev_b32_e32 v86, 16, v87
	v_and_b32_e32 v87, 0xffff0000, v87
	v_pk_fma_f32 v[70:71], v[48:49], v[90:91], v[70:71]
	ds_read2st64_b32 v[72:73], v83 offset0:52 offset1:56
	s_waitcnt lgkmcnt(2)
; DEV float bflo(unsigned u) { return __uint_as_float(u << 16); }
; DEV float bfhi(unsigned u) { return __uint_as_float(u & 0xffff0000u); }
; DEV void conv_tile(const Params& p, int tile, char* smem) {
;     ...
; #pragma unroll 1
;   for (int i = 0; i < 8; i++) {
;     float a0 = bb.x, a1 = bb.y;
; #pragma unroll
;     for (int wi = 0; wi < 31; wi++) {
;       unsigned u = *(const unsigned*)(stg + (i + wi) * 512 + c);
;       a0 += bflo(u) * w0[wi]; a1 += bfhi(u) * w1[wi];
;     }
;     *(float2*)(ybuf + i * 512 + c) = make_float2(a0, a1);
;     float s1 = wave_sum(a0 + a1);
;     float s2 = wave_sum(a0 * a0 + a1 * a1);
	v_lshlrev_b32_e32 v96, 16, v92
	v_and_b32_e32 v97, 0xffff0000, v92
	v_pk_fma_f32 v[70:71], v[50:51], v[86:87], v[70:71]
	v_lshlrev_b32_e32 v92, 16, v93
	v_and_b32_e32 v93, 0xffff0000, v93
	v_pk_fma_f32 v[70:71], v[56:57], v[96:97], v[70:71]
	ds_read2st64_b32 v[88:89], v83 offset0:60 offset1:64
	s_waitcnt lgkmcnt(2)
	v_lshlrev_b32_e32 v98, 16, v94
	v_and_b32_e32 v99, 0xffff0000, v94
	v_pk_fma_f32 v[70:71], v[58:59], v[92:93], v[70:71]
	v_lshlrev_b32_e32 v84, 16, v95
	v_pk_fma_f32 v[70:71], v[66:67], v[98:99], v[70:71]
	v_and_b32_e32 v85, 0xffff0000, v95
	ds_read2st64_b32 v[90:91], v83 offset0:68 offset1:72
	s_waitcnt lgkmcnt(2)
	v_lshlrev_b32_e32 v86, 16, v72
	v_and_b32_e32 v87, 0xffff0000, v72
	v_pk_fma_f32 v[70:71], v[60:61], v[84:85], v[70:71]
	v_lshlrev_b32_e32 v72, 16, v73
	v_and_b32_e32 v73, 0xffff0000, v73
	ds_read2st64_b32 v[96:97], v83 offset0:76 offset1:80
	v_pk_fma_f32 v[70:71], v[4:5], v[86:87], v[70:71]
	s_waitcnt lgkmcnt(2)
	v_lshlrev_b32_e32 v92, 16, v88
	v_and_b32_e32 v93, 0xffff0000, v88
	v_pk_fma_f32 v[70:71], v[6:7], v[72:73], v[70:71]
	v_lshlrev_b32_e32 v88, 16, v89
	v_and_b32_e32 v89, 0xffff0000, v89
	ds_read2st64_b32 v[98:99], v83 offset0:84 offset1:88
	v_pk_fma_f32 v[70:71], v[8:9], v[92:93], v[70:71]
	s_waitcnt lgkmcnt(2)
	v_lshlrev_b32_e32 v94, 16, v90
	v_and_b32_e32 v95, 0xffff0000, v90
	v_pk_fma_f32 v[70:71], v[10:11], v[88:89], v[70:71]
	v_lshlrev_b32_e32 v90, 16, v91
	v_and_b32_e32 v91, 0xffff0000, v91
	v_pk_fma_f32 v[70:71], v[12:13], v[94:95], v[70:71]
	ds_read2st64_b32 v[72:73], v83 offset0:92 offset1:96
	s_waitcnt lgkmcnt(2)
	v_lshlrev_b32_e32 v100, 16, v96
	v_and_b32_e32 v101, 0xffff0000, v96
	v_pk_fma_f32 v[70:71], v[14:15], v[90:91], v[70:71]
	v_lshlrev_b32_e32 v96, 16, v97
	v_and_b32_e32 v97, 0xffff0000, v97
	v_pk_fma_f32 v[70:71], v[16:17], v[100:101], v[70:71]
	ds_read2st64_b32 v[84:85], v83 offset0:100 offset1:104
	s_waitcnt lgkmcnt(2)
	v_lshlrev_b32_e32 v102, 16, v98
	v_and_b32_e32 v103, 0xffff0000, v98
	v_pk_fma_f32 v[70:71], v[20:21], v[96:97], v[70:71]
	v_lshlrev_b32_e32 v98, 16, v99
	v_and_b32_e32 v99, 0xffff0000, v99
	v_pk_fma_f32 v[70:71], v[22:23], v[102:103], v[70:71]
	ds_read2st64_b32 v[90:91], v83 offset0:108 offset1:112
	v_pk_fma_f32 v[70:71], v[24:25], v[98:99], v[70:71]
	s_waitcnt lgkmcnt(2)
	v_lshlrev_b32_e32 v86, 16, v72
	v_and_b32_e32 v87, 0xffff0000, v72
	v_lshlrev_b32_e32 v72, 16, v73
	v_and_b32_e32 v73, 0xffff0000, v73
	ds_read2st64_b32 v[92:93], v83 offset0:116 offset1:120
	v_pk_fma_f32 v[70:71], v[26:27], v[86:87], v[70:71]
	s_waitcnt lgkmcnt(2)
	v_lshlrev_b32_e32 v88, 16, v84
	v_and_b32_e32 v89, 0xffff0000, v84
	v_pk_fma_f32 v[70:71], v[28:29], v[72:73], v[70:71]
	v_lshlrev_b32_e32 v84, 16, v85
	v_and_b32_e32 v85, 0xffff0000, v85
	ds_read2st64_b32 v[98:99], v83 offset0:124 offset1:128
	v_pk_fma_f32 v[70:71], v[30:31], v[88:89], v[70:71]
	s_waitcnt lgkmcnt(2)
	v_lshlrev_b32_e32 v94, 16, v90
	v_and_b32_e32 v95, 0xffff0000, v90
	v_pk_fma_f32 v[70:71], v[32:33], v[84:85], v[70:71]
	v_lshlrev_b32_e32 v90, 16, v91
	v_and_b32_e32 v91, 0xffff0000, v91
	ds_read_b32 v103, v83 offset:33792
	v_pk_fma_f32 v[70:71], v[34:35], v[94:95], v[70:71]
	s_waitcnt lgkmcnt(2)
	v_lshlrev_b32_e32 v96, 16, v92
	v_and_b32_e32 v97, 0xffff0000, v92
	v_pk_fma_f32 v[70:71], v[36:37], v[90:91], v[70:71]
	v_lshlrev_b32_e32 v92, 16, v93
	v_and_b32_e32 v93, 0xffff0000, v93
	v_pk_fma_f32 v[70:71], v[38:39], v[96:97], v[70:71]
	s_waitcnt lgkmcnt(1)
	v_lshlrev_b32_e32 v100, 16, v98
	v_and_b32_e32 v101, 0xffff0000, v98
	v_pk_fma_f32 v[70:71], v[40:41], v[92:93], v[70:71]
	v_lshlrev_b32_e32 v98, 16, v99
	v_and_b32_e32 v99, 0xffff0000, v99
	v_pk_fma_f32 v[70:71], v[42:43], v[100:101], v[70:71]
	s_waitcnt lgkmcnt(0)
	v_lshlrev_b32_e32 v102, 16, v103
	v_and_b32_e32 v103, 0xffff0000, v103
	v_pk_fma_f32 v[70:71], v[44:45], v[98:99], v[70:71]
	s_nop 0
	v_pk_fma_f32 v[70:71], v[46:47], v[102:103], v[70:71]
	ds_write_b64 v82, v[70:71] offset:6144
	v_pk_mul_f32 v[72:73], v[70:71], v[70:71]
	v_mov_b32_e32 v84, v71
	v_mov_b32_e32 v85, v73
	v_mov_b32_e32 v71, v72
	v_pk_add_f32 v[110:111], v[84:85], v[70:71]
	ds_read2st64_b32 v[70:71], v83 offset0:16 offset1:20
	s_waitcnt lgkmcnt(1)
	ds_read2st64_b32 v[72:73], v83 offset0:24 offset1:28
	ds_read2st64_b32 v[86:87], v83 offset0:32 offset1:36
	ds_read2st64_b32 v[92:93], v83 offset0:40 offset1:44
	ds_read2st64_b32 v[94:95], v83 offset0:48 offset1:52
	s_waitcnt lgkmcnt(4)
	v_lshlrev_b32_e32 v84, 16, v70
	v_and_b32_e32 v85, 0xffff0000, v70
	v_lshlrev_b32_e32 v70, 16, v71
	v_and_b32_e32 v71, 0xffff0000, v71
	s_waitcnt vmcnt(0)
	v_pk_fma_f32 v[84:85], v[62:63], v[84:85], v[68:69]
	s_waitcnt lgkmcnt(3)
	v_lshlrev_b32_e32 v88, 16, v72
	v_and_b32_e32 v89, 0xffff0000, v72
	v_pk_fma_f32 v[70:71], v[64:65], v[70:71], v[84:85]
	v_lshlrev_b32_e32 v72, 16, v73
	v_and_b32_e32 v73, 0xffff0000, v73
	v_pk_fma_f32 v[70:71], v[52:53], v[88:89], v[70:71]
	s_waitcnt lgkmcnt(2)
	v_lshlrev_b32_e32 v90, 16, v86
	v_and_b32_e32 v91, 0xffff0000, v86
	v_pk_fma_f32 v[70:71], v[54:55], v[72:73], v[70:71]
	v_lshlrev_b32_e32 v86, 16, v87
	v_and_b32_e32 v87, 0xffff0000, v87
	v_pk_fma_f32 v[70:71], v[48:49], v[90:91], v[70:71]
	ds_read2st64_b32 v[72:73], v83 offset0:56 offset1:60
	s_waitcnt lgkmcnt(2)
	v_lshlrev_b32_e32 v96, 16, v92
	v_and_b32_e32 v97, 0xffff0000, v92
	v_pk_fma_f32 v[70:71], v[50:51], v[86:87], v[70:71]
	v_lshlrev_b32_e32 v92, 16, v93
	v_and_b32_e32 v93, 0xffff0000, v93
	v_pk_fma_f32 v[70:71], v[56:57], v[96:97], v[70:71]
	ds_read2st64_b32 v[88:89], v83 offset0:64 offset1:68
	s_waitcnt lgkmcnt(2)
; DEV float bflo(unsigned u) { return __uint_as_float(u << 16); }
; DEV float bfhi(unsigned u) { return __uint_as_float(u & 0xffff0000u); }
; DEV void conv_tile(const Params& p, int tile, char* smem) {
;     ...
; #pragma unroll 1
;   for (int i = 0; i < 8; i++) {
;     float a0 = bb.x, a1 = bb.y;
; #pragma unroll
;     for (int wi = 0; wi < 31; wi++) {
;       unsigned u = *(const unsigned*)(stg + (i + wi) * 512 + c);
;       a0 += bflo(u) * w0[wi]; a1 += bfhi(u) * w1[wi];
;     }
;     *(float2*)(ybuf + i * 512 + c) = make_float2(a0, a1);
;     float s1 = wave_sum(a0 + a1);
;     float s2 = wave_sum(a0 * a0 + a1 * a1);
	v_lshlrev_b32_e32 v98, 16, v94
	v_and_b32_e32 v99, 0xffff0000, v94
	v_pk_fma_f32 v[70:71], v[58:59], v[92:93], v[70:71]
	v_lshlrev_b32_e32 v84, 16, v95
	v_pk_fma_f32 v[70:71], v[66:67], v[98:99], v[70:71]
	v_and_b32_e32 v85, 0xffff0000, v95
	ds_read2st64_b32 v[90:91], v83 offset0:72 offset1:76
	s_waitcnt lgkmcnt(2)
	v_lshlrev_b32_e32 v86, 16, v72
	v_and_b32_e32 v87, 0xffff0000, v72
	v_pk_fma_f32 v[70:71], v[60:61], v[84:85], v[70:71]
	v_lshlrev_b32_e32 v72, 16, v73
	v_and_b32_e32 v73, 0xffff0000, v73
	ds_read2st64_b32 v[96:97], v83 offset0:80 offset1:84
	v_pk_fma_f32 v[70:71], v[4:5], v[86:87], v[70:71]
	s_waitcnt lgkmcnt(2)
	v_lshlrev_b32_e32 v92, 16, v88
	v_and_b32_e32 v93, 0xffff0000, v88
	v_pk_fma_f32 v[70:71], v[6:7], v[72:73], v[70:71]
	v_lshlrev_b32_e32 v88, 16, v89
	v_and_b32_e32 v89, 0xffff0000, v89
	ds_read2st64_b32 v[98:99], v83 offset0:88 offset1:92
	v_pk_fma_f32 v[70:71], v[8:9], v[92:93], v[70:71]
	s_waitcnt lgkmcnt(2)
	v_lshlrev_b32_e32 v94, 16, v90
	v_and_b32_e32 v95, 0xffff0000, v90
	v_pk_fma_f32 v[70:71], v[10:11], v[88:89], v[70:71]
	v_lshlrev_b32_e32 v90, 16, v91
	v_and_b32_e32 v91, 0xffff0000, v91
	v_pk_fma_f32 v[70:71], v[12:13], v[94:95], v[70:71]
	ds_read2st64_b32 v[72:73], v83 offset0:96 offset1:100
	s_waitcnt lgkmcnt(2)
	v_lshlrev_b32_e32 v100, 16, v96
	v_and_b32_e32 v101, 0xffff0000, v96
	v_pk_fma_f32 v[70:71], v[14:15], v[90:91], v[70:71]
	v_lshlrev_b32_e32 v96, 16, v97
	v_and_b32_e32 v97, 0xffff0000, v97
	v_pk_fma_f32 v[70:71], v[16:17], v[100:101], v[70:71]
	ds_read2st64_b32 v[84:85], v83 offset0:104 offset1:108
	s_waitcnt lgkmcnt(2)
	v_lshlrev_b32_e32 v102, 16, v98
	v_and_b32_e32 v103, 0xffff0000, v98
	v_pk_fma_f32 v[70:71], v[20:21], v[96:97], v[70:71]
	v_lshlrev_b32_e32 v98, 16, v99
	v_and_b32_e32 v99, 0xffff0000, v99
	v_pk_fma_f32 v[70:71], v[22:23], v[102:103], v[70:71]
	ds_read2st64_b32 v[90:91], v83 offset0:112 offset1:116
	v_pk_fma_f32 v[70:71], v[24:25], v[98:99], v[70:71]
	s_waitcnt lgkmcnt(2)
	v_lshlrev_b32_e32 v86, 16, v72
	v_and_b32_e32 v87, 0xffff0000, v72
	v_lshlrev_b32_e32 v72, 16, v73
	v_and_b32_e32 v73, 0xffff0000, v73
	ds_read2st64_b32 v[92:93], v83 offset0:120 offset1:124
	v_pk_fma_f32 v[70:71], v[26:27], v[86:87], v[70:71]
	s_waitcnt lgkmcnt(2)
	v_lshlrev_b32_e32 v88, 16, v84
	v_and_b32_e32 v89, 0xffff0000, v84
	v_pk_fma_f32 v[70:71], v[28:29], v[72:73], v[70:71]
	v_lshlrev_b32_e32 v84, 16, v85
	v_and_b32_e32 v85, 0xffff0000, v85
	ds_read2st64_b32 v[98:99], v83 offset0:128 offset1:132
	v_pk_fma_f32 v[70:71], v[30:31], v[88:89], v[70:71]
	s_waitcnt lgkmcnt(2)
	v_lshlrev_b32_e32 v94, 16, v90
	v_and_b32_e32 v95, 0xffff0000, v90
	v_pk_fma_f32 v[70:71], v[32:33], v[84:85], v[70:71]
	v_lshlrev_b32_e32 v90, 16, v91
	v_and_b32_e32 v91, 0xffff0000, v91
	ds_read_b32 v103, v83 offset:34816
	v_pk_fma_f32 v[70:71], v[34:35], v[94:95], v[70:71]
	s_waitcnt lgkmcnt(2)
	v_lshlrev_b32_e32 v96, 16, v92
	v_and_b32_e32 v97, 0xffff0000, v92
	v_pk_fma_f32 v[70:71], v[36:37], v[90:91], v[70:71]
	v_lshlrev_b32_e32 v92, 16, v93
	v_and_b32_e32 v93, 0xffff0000, v93
	v_pk_fma_f32 v[70:71], v[38:39], v[96:97], v[70:71]
	s_waitcnt lgkmcnt(1)
	v_lshlrev_b32_e32 v100, 16, v98
	v_and_b32_e32 v101, 0xffff0000, v98
	v_pk_fma_f32 v[70:71], v[40:41], v[92:93], v[70:71]
	v_lshlrev_b32_e32 v98, 16, v99
	v_and_b32_e32 v99, 0xffff0000, v99
	v_pk_fma_f32 v[70:71], v[42:43], v[100:101], v[70:71]
	s_waitcnt lgkmcnt(0)
	v_lshlrev_b32_e32 v102, 16, v103
	v_and_b32_e32 v103, 0xffff0000, v103
	v_pk_fma_f32 v[70:71], v[44:45], v[98:99], v[70:71]
	s_nop 0
	v_pk_fma_f32 v[70:71], v[46:47], v[102:103], v[70:71]
	ds_write_b64 v82, v[70:71] offset:8192
	v_pk_mul_f32 v[72:73], v[70:71], v[70:71]
	v_mov_b32_e32 v84, v71
	v_mov_b32_e32 v85, v73
	v_mov_b32_e32 v71, v72
	v_pk_add_f32 v[112:113], v[84:85], v[70:71]
	ds_read2st64_b32 v[70:71], v83 offset0:20 offset1:24
	s_waitcnt lgkmcnt(1)
	ds_read2st64_b32 v[72:73], v83 offset0:28 offset1:32
	ds_read2st64_b32 v[86:87], v83 offset0:36 offset1:40
	ds_read2st64_b32 v[92:93], v83 offset0:44 offset1:48
	ds_read2st64_b32 v[94:95], v83 offset0:52 offset1:56
	s_waitcnt lgkmcnt(4)
	v_lshlrev_b32_e32 v84, 16, v70
	v_and_b32_e32 v85, 0xffff0000, v70
	v_lshlrev_b32_e32 v70, 16, v71
	v_and_b32_e32 v71, 0xffff0000, v71
	s_waitcnt vmcnt(0)
	v_pk_fma_f32 v[84:85], v[62:63], v[84:85], v[68:69]
	s_waitcnt lgkmcnt(3)
	v_lshlrev_b32_e32 v88, 16, v72
	v_and_b32_e32 v89, 0xffff0000, v72
	v_pk_fma_f32 v[70:71], v[64:65], v[70:71], v[84:85]
	v_lshlrev_b32_e32 v72, 16, v73
	v_and_b32_e32 v73, 0xffff0000, v73
	v_pk_fma_f32 v[70:71], v[52:53], v[88:89], v[70:71]
	s_waitcnt lgkmcnt(2)
	v_lshlrev_b32_e32 v90, 16, v86
	v_and_b32_e32 v91, 0xffff0000, v86
	v_pk_fma_f32 v[70:71], v[54:55], v[72:73], v[70:71]
	v_lshlrev_b32_e32 v86, 16, v87
	v_and_b32_e32 v87, 0xffff0000, v87
	v_pk_fma_f32 v[70:71], v[48:49], v[90:91], v[70:71]
	ds_read2st64_b32 v[72:73], v83 offset0:60 offset1:64
	s_waitcnt lgkmcnt(2)
	v_lshlrev_b32_e32 v96, 16, v92
	v_and_b32_e32 v97, 0xffff0000, v92
	v_pk_fma_f32 v[70:71], v[50:51], v[86:87], v[70:71]
	v_lshlrev_b32_e32 v92, 16, v93
	v_and_b32_e32 v93, 0xffff0000, v93
	v_pk_fma_f32 v[70:71], v[56:57], v[96:97], v[70:71]
	ds_read2st64_b32 v[88:89], v83 offset0:68 offset1:72
	s_waitcnt lgkmcnt(2)
	v_lshlrev_b32_e32 v98, 16, v94
	v_and_b32_e32 v99, 0xffff0000, v94
	v_pk_fma_f32 v[70:71], v[58:59], v[92:93], v[70:71]
	v_lshlrev_b32_e32 v84, 16, v95
	v_pk_fma_f32 v[70:71], v[66:67], v[98:99], v[70:71]
	v_and_b32_e32 v85, 0xffff0000, v95
	ds_read2st64_b32 v[90:91], v83 offset0:76 offset1:80
	s_waitcnt lgkmcnt(2)
; DEV float bflo(unsigned u) { return __uint_as_float(u << 16); }
; DEV float bfhi(unsigned u) { return __uint_as_float(u & 0xffff0000u); }
; DEV void conv_tile(const Params& p, int tile, char* smem) {
;     ...
; #pragma unroll 1
;   for (int i = 0; i < 8; i++) {
;     float a0 = bb.x, a1 = bb.y;
; #pragma unroll
;     for (int wi = 0; wi < 31; wi++) {
;       unsigned u = *(const unsigned*)(stg + (i + wi) * 512 + c);
;       a0 += bflo(u) * w0[wi]; a1 += bfhi(u) * w1[wi];
;     }
;     *(float2*)(ybuf + i * 512 + c) = make_float2(a0, a1);
;     float s1 = wave_sum(a0 + a1);
;     float s2 = wave_sum(a0 * a0 + a1 * a1);
	v_lshlrev_b32_e32 v86, 16, v72
	v_and_b32_e32 v87, 0xffff0000, v72
	v_pk_fma_f32 v[70:71], v[60:61], v[84:85], v[70:71]
	v_lshlrev_b32_e32 v72, 16, v73
	v_and_b32_e32 v73, 0xffff0000, v73
	ds_read2st64_b32 v[96:97], v83 offset0:84 offset1:88
	v_pk_fma_f32 v[70:71], v[4:5], v[86:87], v[70:71]
	s_waitcnt lgkmcnt(2)
	v_lshlrev_b32_e32 v92, 16, v88
	v_and_b32_e32 v93, 0xffff0000, v88
	v_pk_fma_f32 v[70:71], v[6:7], v[72:73], v[70:71]
	v_lshlrev_b32_e32 v88, 16, v89
	v_and_b32_e32 v89, 0xffff0000, v89
	ds_read2st64_b32 v[98:99], v83 offset0:92 offset1:96
	v_pk_fma_f32 v[70:71], v[8:9], v[92:93], v[70:71]
	s_waitcnt lgkmcnt(2)
	v_lshlrev_b32_e32 v94, 16, v90
	v_and_b32_e32 v95, 0xffff0000, v90
	v_pk_fma_f32 v[70:71], v[10:11], v[88:89], v[70:71]
	v_lshlrev_b32_e32 v90, 16, v91
	v_and_b32_e32 v91, 0xffff0000, v91
	v_pk_fma_f32 v[70:71], v[12:13], v[94:95], v[70:71]
	ds_read2st64_b32 v[72:73], v83 offset0:100 offset1:104
	s_waitcnt lgkmcnt(2)
	v_lshlrev_b32_e32 v100, 16, v96
	v_and_b32_e32 v101, 0xffff0000, v96
	v_pk_fma_f32 v[70:71], v[14:15], v[90:91], v[70:71]
	v_lshlrev_b32_e32 v96, 16, v97
	v_and_b32_e32 v97, 0xffff0000, v97
	v_pk_fma_f32 v[70:71], v[16:17], v[100:101], v[70:71]
	ds_read2st64_b32 v[84:85], v83 offset0:108 offset1:112
	s_waitcnt lgkmcnt(2)
	v_lshlrev_b32_e32 v102, 16, v98
	v_and_b32_e32 v103, 0xffff0000, v98
	v_pk_fma_f32 v[70:71], v[20:21], v[96:97], v[70:71]
	v_lshlrev_b32_e32 v98, 16, v99
	v_and_b32_e32 v99, 0xffff0000, v99
	v_pk_fma_f32 v[70:71], v[22:23], v[102:103], v[70:71]
	ds_read2st64_b32 v[90:91], v83 offset0:116 offset1:120
	v_pk_fma_f32 v[70:71], v[24:25], v[98:99], v[70:71]
	s_waitcnt lgkmcnt(2)
	v_lshlrev_b32_e32 v86, 16, v72
	v_and_b32_e32 v87, 0xffff0000, v72
	v_lshlrev_b32_e32 v72, 16, v73
	v_and_b32_e32 v73, 0xffff0000, v73
	ds_read2st64_b32 v[92:93], v83 offset0:124 offset1:128
	v_pk_fma_f32 v[70:71], v[26:27], v[86:87], v[70:71]
	s_waitcnt lgkmcnt(2)
	v_lshlrev_b32_e32 v88, 16, v84
	v_and_b32_e32 v89, 0xffff0000, v84
	v_pk_fma_f32 v[70:71], v[28:29], v[72:73], v[70:71]
	v_lshlrev_b32_e32 v84, 16, v85
	v_and_b32_e32 v85, 0xffff0000, v85
	ds_read2st64_b32 v[98:99], v83 offset0:132 offset1:136
	v_pk_fma_f32 v[70:71], v[30:31], v[88:89], v[70:71]
	s_waitcnt lgkmcnt(2)
	v_lshlrev_b32_e32 v94, 16, v90
	v_and_b32_e32 v95, 0xffff0000, v90
	v_pk_fma_f32 v[70:71], v[32:33], v[84:85], v[70:71]
	v_lshlrev_b32_e32 v90, 16, v91
	v_and_b32_e32 v91, 0xffff0000, v91
	ds_read_b32 v103, v83 offset:35840
	v_pk_fma_f32 v[70:71], v[34:35], v[94:95], v[70:71]
	s_waitcnt lgkmcnt(2)
	v_lshlrev_b32_e32 v96, 16, v92
	v_and_b32_e32 v97, 0xffff0000, v92
	v_pk_fma_f32 v[70:71], v[36:37], v[90:91], v[70:71]
	v_lshlrev_b32_e32 v92, 16, v93
	v_and_b32_e32 v93, 0xffff0000, v93
	v_pk_fma_f32 v[70:71], v[38:39], v[96:97], v[70:71]
	s_waitcnt lgkmcnt(1)
	v_lshlrev_b32_e32 v100, 16, v98
	v_and_b32_e32 v101, 0xffff0000, v98
	v_pk_fma_f32 v[70:71], v[40:41], v[92:93], v[70:71]
	v_lshlrev_b32_e32 v98, 16, v99
	v_and_b32_e32 v99, 0xffff0000, v99
	v_pk_fma_f32 v[70:71], v[42:43], v[100:101], v[70:71]
	s_waitcnt lgkmcnt(0)
	v_lshlrev_b32_e32 v102, 16, v103
	v_and_b32_e32 v103, 0xffff0000, v103
	v_pk_fma_f32 v[70:71], v[44:45], v[98:99], v[70:71]
	s_nop 0
	v_pk_fma_f32 v[70:71], v[46:47], v[102:103], v[70:71]
	ds_write_b64 v82, v[70:71] offset:10240
	v_pk_mul_f32 v[72:73], v[70:71], v[70:71]
	v_mov_b32_e32 v84, v71
	v_mov_b32_e32 v85, v73
	v_mov_b32_e32 v71, v72
	v_pk_add_f32 v[114:115], v[84:85], v[70:71]
	ds_read2st64_b32 v[70:71], v83 offset0:24 offset1:28
	s_waitcnt lgkmcnt(1)
	ds_read2st64_b32 v[72:73], v83 offset0:32 offset1:36
	ds_read2st64_b32 v[86:87], v83 offset0:40 offset1:44
	ds_read2st64_b32 v[92:93], v83 offset0:48 offset1:52
	ds_read2st64_b32 v[94:95], v83 offset0:56 offset1:60
	s_waitcnt lgkmcnt(4)
	v_lshlrev_b32_e32 v84, 16, v70
	v_and_b32_e32 v85, 0xffff0000, v70
	v_lshlrev_b32_e32 v70, 16, v71
	v_and_b32_e32 v71, 0xffff0000, v71
	s_waitcnt vmcnt(0)
	v_pk_fma_f32 v[84:85], v[62:63], v[84:85], v[68:69]
	s_waitcnt lgkmcnt(3)
	v_lshlrev_b32_e32 v88, 16, v72
	v_and_b32_e32 v89, 0xffff0000, v72
	v_pk_fma_f32 v[70:71], v[64:65], v[70:71], v[84:85]
	v_lshlrev_b32_e32 v72, 16, v73
	v_and_b32_e32 v73, 0xffff0000, v73
	v_pk_fma_f32 v[70:71], v[52:53], v[88:89], v[70:71]
	s_waitcnt lgkmcnt(2)
	v_lshlrev_b32_e32 v90, 16, v86
	v_and_b32_e32 v91, 0xffff0000, v86
	v_pk_fma_f32 v[70:71], v[54:55], v[72:73], v[70:71]
	v_lshlrev_b32_e32 v86, 16, v87
	v_and_b32_e32 v87, 0xffff0000, v87
	v_pk_fma_f32 v[70:71], v[48:49], v[90:91], v[70:71]
	ds_read2st64_b32 v[72:73], v83 offset0:64 offset1:68
	s_waitcnt lgkmcnt(2)
	v_lshlrev_b32_e32 v96, 16, v92
	v_and_b32_e32 v97, 0xffff0000, v92
	v_pk_fma_f32 v[70:71], v[50:51], v[86:87], v[70:71]
	v_lshlrev_b32_e32 v92, 16, v93
	v_and_b32_e32 v93, 0xffff0000, v93
	v_pk_fma_f32 v[70:71], v[56:57], v[96:97], v[70:71]
	ds_read2st64_b32 v[88:89], v83 offset0:72 offset1:76
	s_waitcnt lgkmcnt(2)
	v_lshlrev_b32_e32 v98, 16, v94
	v_and_b32_e32 v99, 0xffff0000, v94
	v_pk_fma_f32 v[70:71], v[58:59], v[92:93], v[70:71]
	v_lshlrev_b32_e32 v84, 16, v95
	v_pk_fma_f32 v[70:71], v[66:67], v[98:99], v[70:71]
	v_and_b32_e32 v85, 0xffff0000, v95
	ds_read2st64_b32 v[90:91], v83 offset0:80 offset1:84
	s_waitcnt lgkmcnt(2)
	v_lshlrev_b32_e32 v86, 16, v72
	v_and_b32_e32 v87, 0xffff0000, v72
	v_pk_fma_f32 v[70:71], v[60:61], v[84:85], v[70:71]
	v_lshlrev_b32_e32 v72, 16, v73
	v_and_b32_e32 v73, 0xffff0000, v73
	ds_read2st64_b32 v[96:97], v83 offset0:88 offset1:92
	v_pk_fma_f32 v[70:71], v[4:5], v[86:87], v[70:71]
	s_waitcnt lgkmcnt(2)
; DEV float bflo(unsigned u) { return __uint_as_float(u << 16); }
; DEV float bfhi(unsigned u) { return __uint_as_float(u & 0xffff0000u); }
; DEV void conv_tile(const Params& p, int tile, char* smem) {
;     ...
; #pragma unroll 1
;   for (int i = 0; i < 8; i++) {
;     float a0 = bb.x, a1 = bb.y;
; #pragma unroll
;     for (int wi = 0; wi < 31; wi++) {
;       unsigned u = *(const unsigned*)(stg + (i + wi) * 512 + c);
;       a0 += bflo(u) * w0[wi]; a1 += bfhi(u) * w1[wi];
;     }
;     *(float2*)(ybuf + i * 512 + c) = make_float2(a0, a1);
;     float s1 = wave_sum(a0 + a1);
;     float s2 = wave_sum(a0 * a0 + a1 * a1);
	v_lshlrev_b32_e32 v92, 16, v88
	v_and_b32_e32 v93, 0xffff0000, v88
	v_pk_fma_f32 v[70:71], v[6:7], v[72:73], v[70:71]
	v_lshlrev_b32_e32 v88, 16, v89
	v_and_b32_e32 v89, 0xffff0000, v89
	ds_read2st64_b32 v[98:99], v83 offset0:96 offset1:100
	v_pk_fma_f32 v[70:71], v[8:9], v[92:93], v[70:71]
	s_waitcnt lgkmcnt(2)
	v_lshlrev_b32_e32 v94, 16, v90
	v_and_b32_e32 v95, 0xffff0000, v90
	v_pk_fma_f32 v[70:71], v[10:11], v[88:89], v[70:71]
	v_lshlrev_b32_e32 v90, 16, v91
	v_and_b32_e32 v91, 0xffff0000, v91
	v_pk_fma_f32 v[70:71], v[12:13], v[94:95], v[70:71]
	ds_read2st64_b32 v[72:73], v83 offset0:104 offset1:108
	s_waitcnt lgkmcnt(2)
	v_lshlrev_b32_e32 v100, 16, v96
	v_and_b32_e32 v101, 0xffff0000, v96
	v_pk_fma_f32 v[70:71], v[14:15], v[90:91], v[70:71]
	v_lshlrev_b32_e32 v96, 16, v97
	v_and_b32_e32 v97, 0xffff0000, v97
	v_pk_fma_f32 v[70:71], v[16:17], v[100:101], v[70:71]
	ds_read2st64_b32 v[84:85], v83 offset0:112 offset1:116
	s_waitcnt lgkmcnt(2)
	v_lshlrev_b32_e32 v102, 16, v98
	v_and_b32_e32 v103, 0xffff0000, v98
	v_pk_fma_f32 v[70:71], v[20:21], v[96:97], v[70:71]
	v_lshlrev_b32_e32 v98, 16, v99
	v_and_b32_e32 v99, 0xffff0000, v99
	v_pk_fma_f32 v[70:71], v[22:23], v[102:103], v[70:71]
	ds_read2st64_b32 v[90:91], v83 offset0:120 offset1:124
	v_pk_fma_f32 v[70:71], v[24:25], v[98:99], v[70:71]
	s_waitcnt lgkmcnt(2)
	v_lshlrev_b32_e32 v86, 16, v72
	v_and_b32_e32 v87, 0xffff0000, v72
	v_lshlrev_b32_e32 v72, 16, v73
	v_and_b32_e32 v73, 0xffff0000, v73
	ds_read2st64_b32 v[92:93], v83 offset0:128 offset1:132
	v_pk_fma_f32 v[70:71], v[26:27], v[86:87], v[70:71]
	s_waitcnt lgkmcnt(2)
	v_lshlrev_b32_e32 v88, 16, v84
	v_and_b32_e32 v89, 0xffff0000, v84
	v_pk_fma_f32 v[70:71], v[28:29], v[72:73], v[70:71]
	v_lshlrev_b32_e32 v84, 16, v85
	v_and_b32_e32 v85, 0xffff0000, v85
	ds_read2st64_b32 v[98:99], v83 offset0:136 offset1:140
	v_pk_fma_f32 v[70:71], v[30:31], v[88:89], v[70:71]
	s_waitcnt lgkmcnt(2)
	v_lshlrev_b32_e32 v94, 16, v90
	v_and_b32_e32 v95, 0xffff0000, v90
	v_pk_fma_f32 v[70:71], v[32:33], v[84:85], v[70:71]
	v_lshlrev_b32_e32 v90, 16, v91
	v_and_b32_e32 v91, 0xffff0000, v91
	ds_read_b32 v103, v83 offset:36864
	v_pk_fma_f32 v[70:71], v[34:35], v[94:95], v[70:71]
	s_waitcnt lgkmcnt(2)
	v_lshlrev_b32_e32 v96, 16, v92
	v_and_b32_e32 v97, 0xffff0000, v92
	v_pk_fma_f32 v[70:71], v[36:37], v[90:91], v[70:71]
	v_lshlrev_b32_e32 v92, 16, v93
	v_and_b32_e32 v93, 0xffff0000, v93
	v_pk_fma_f32 v[70:71], v[38:39], v[96:97], v[70:71]
	s_waitcnt lgkmcnt(1)
	v_lshlrev_b32_e32 v100, 16, v98
	v_and_b32_e32 v101, 0xffff0000, v98
	v_pk_fma_f32 v[70:71], v[40:41], v[92:93], v[70:71]
	v_lshlrev_b32_e32 v98, 16, v99
	v_and_b32_e32 v99, 0xffff0000, v99
	v_pk_fma_f32 v[70:71], v[42:43], v[100:101], v[70:71]
	s_waitcnt lgkmcnt(0)
	v_lshlrev_b32_e32 v102, 16, v103
	v_and_b32_e32 v103, 0xffff0000, v103
	v_pk_fma_f32 v[70:71], v[44:45], v[98:99], v[70:71]
	s_nop 0
	v_pk_fma_f32 v[70:71], v[46:47], v[102:103], v[70:71]
	ds_write_b64 v82, v[70:71] offset:12288
	v_pk_mul_f32 v[72:73], v[70:71], v[70:71]
	v_mov_b32_e32 v84, v71
	v_mov_b32_e32 v85, v73
	v_mov_b32_e32 v71, v72
	v_pk_add_f32 v[116:117], v[84:85], v[70:71]
	ds_read2st64_b32 v[70:71], v83 offset0:28 offset1:32
	s_waitcnt lgkmcnt(1)
	ds_read2st64_b32 v[72:73], v83 offset0:36 offset1:40
	ds_read2st64_b32 v[86:87], v83 offset0:44 offset1:48
	ds_read2st64_b32 v[92:93], v83 offset0:52 offset1:56
	ds_read2st64_b32 v[94:95], v83 offset0:60 offset1:64
	s_waitcnt lgkmcnt(4)
	v_lshlrev_b32_e32 v84, 16, v70
	v_and_b32_e32 v85, 0xffff0000, v70
	v_lshlrev_b32_e32 v70, 16, v71
	v_and_b32_e32 v71, 0xffff0000, v71
	s_waitcnt vmcnt(0)
	v_pk_fma_f32 v[84:85], v[62:63], v[84:85], v[68:69]
	s_waitcnt lgkmcnt(3)
	v_lshlrev_b32_e32 v88, 16, v72
	v_and_b32_e32 v89, 0xffff0000, v72
	v_pk_fma_f32 v[70:71], v[64:65], v[70:71], v[84:85]
	v_lshlrev_b32_e32 v72, 16, v73
	v_and_b32_e32 v73, 0xffff0000, v73
	v_pk_fma_f32 v[70:71], v[52:53], v[88:89], v[70:71]
	s_waitcnt lgkmcnt(2)
	v_lshlrev_b32_e32 v90, 16, v86
	v_and_b32_e32 v91, 0xffff0000, v86
	v_pk_fma_f32 v[70:71], v[54:55], v[72:73], v[70:71]
	v_lshlrev_b32_e32 v86, 16, v87
	v_and_b32_e32 v87, 0xffff0000, v87
	v_pk_fma_f32 v[70:71], v[48:49], v[90:91], v[70:71]
	ds_read2st64_b32 v[72:73], v83 offset0:68 offset1:72
	s_waitcnt lgkmcnt(2)
	v_lshlrev_b32_e32 v96, 16, v92
	v_and_b32_e32 v97, 0xffff0000, v92
	v_pk_fma_f32 v[70:71], v[50:51], v[86:87], v[70:71]
	v_lshlrev_b32_e32 v92, 16, v93
	v_and_b32_e32 v93, 0xffff0000, v93
	v_pk_fma_f32 v[70:71], v[56:57], v[96:97], v[70:71]
	ds_read2st64_b32 v[88:89], v83 offset0:76 offset1:80
	s_waitcnt lgkmcnt(2)
	v_lshlrev_b32_e32 v98, 16, v94
	v_and_b32_e32 v99, 0xffff0000, v94
	v_pk_fma_f32 v[70:71], v[58:59], v[92:93], v[70:71]
	v_lshlrev_b32_e32 v84, 16, v95
	v_pk_fma_f32 v[70:71], v[66:67], v[98:99], v[70:71]
	v_and_b32_e32 v85, 0xffff0000, v95
	ds_read2st64_b32 v[90:91], v83 offset0:84 offset1:88
	s_waitcnt lgkmcnt(2)
	v_lshlrev_b32_e32 v86, 16, v72
	v_and_b32_e32 v87, 0xffff0000, v72
	v_pk_fma_f32 v[70:71], v[60:61], v[84:85], v[70:71]
	v_lshlrev_b32_e32 v72, 16, v73
	v_and_b32_e32 v73, 0xffff0000, v73
	ds_read2st64_b32 v[96:97], v83 offset0:92 offset1:96
	v_pk_fma_f32 v[70:71], v[4:5], v[86:87], v[70:71]
	s_waitcnt lgkmcnt(2)
	v_lshlrev_b32_e32 v92, 16, v88
	v_and_b32_e32 v93, 0xffff0000, v88
	v_pk_fma_f32 v[70:71], v[6:7], v[72:73], v[70:71]
	v_lshlrev_b32_e32 v88, 16, v89
	v_and_b32_e32 v89, 0xffff0000, v89
	ds_read2st64_b32 v[98:99], v83 offset0:100 offset1:104
	v_pk_fma_f32 v[70:71], v[8:9], v[92:93], v[70:71]
	s_waitcnt lgkmcnt(2)
; DEV float bflo(unsigned u) { return __uint_as_float(u << 16); }
; DEV float bfhi(unsigned u) { return __uint_as_float(u & 0xffff0000u); }
; DEV float wave_sum(float v) {
; #pragma unroll
;   for (int o = 32; o > 0; o >>= 1) v += __shfl_xor(v, o);
;   return v;
; DEV void conv_tile(const Params& p, int tile, char* smem) {
;     ...
; #pragma unroll 1
;   for (int i = 0; i < 8; i++) {
;     float a0 = bb.x, a1 = bb.y;
; #pragma unroll
;     for (int wi = 0; wi < 31; wi++) {
;       unsigned u = *(const unsigned*)(stg + (i + wi) * 512 + c);
;       a0 += bflo(u) * w0[wi]; a1 += bfhi(u) * w1[wi];
;     }
;     *(float2*)(ybuf + i * 512 + c) = make_float2(a0, a1);
;     float s1 = wave_sum(a0 + a1);
;     float s2 = wave_sum(a0 * a0 + a1 * a1);
;     if (lane == 0) { red[(i * 4 + w) * 2] = s1; red[(i * 4 + w) * 2 + 1] = s2; }
	v_lshlrev_b32_e32 v94, 16, v90
	v_and_b32_e32 v95, 0xffff0000, v90
	v_pk_fma_f32 v[70:71], v[10:11], v[88:89], v[70:71]
	v_lshlrev_b32_e32 v90, 16, v91
	v_and_b32_e32 v91, 0xffff0000, v91
	v_pk_fma_f32 v[70:71], v[12:13], v[94:95], v[70:71]
	ds_read2st64_b32 v[72:73], v83 offset0:108 offset1:112
	s_waitcnt lgkmcnt(2)
	v_lshlrev_b32_e32 v100, 16, v96
	v_and_b32_e32 v101, 0xffff0000, v96
	v_pk_fma_f32 v[70:71], v[14:15], v[90:91], v[70:71]
	v_lshlrev_b32_e32 v96, 16, v97
	v_and_b32_e32 v97, 0xffff0000, v97
	v_pk_fma_f32 v[70:71], v[16:17], v[100:101], v[70:71]
	ds_read2st64_b32 v[84:85], v83 offset0:116 offset1:120
	s_waitcnt lgkmcnt(2)
	v_lshlrev_b32_e32 v102, 16, v98
	v_and_b32_e32 v103, 0xffff0000, v98
	v_pk_fma_f32 v[70:71], v[20:21], v[96:97], v[70:71]
	v_lshlrev_b32_e32 v98, 16, v99
	v_and_b32_e32 v99, 0xffff0000, v99
	v_pk_fma_f32 v[70:71], v[22:23], v[102:103], v[70:71]
	ds_read2st64_b32 v[90:91], v83 offset0:124 offset1:128
	v_pk_fma_f32 v[70:71], v[24:25], v[98:99], v[70:71]
	s_waitcnt lgkmcnt(2)
	v_lshlrev_b32_e32 v86, 16, v72
	v_and_b32_e32 v87, 0xffff0000, v72
	v_lshlrev_b32_e32 v72, 16, v73
	v_and_b32_e32 v73, 0xffff0000, v73
	ds_read2st64_b32 v[92:93], v83 offset0:132 offset1:136
	v_pk_fma_f32 v[70:71], v[26:27], v[86:87], v[70:71]
	s_waitcnt lgkmcnt(2)
	v_lshlrev_b32_e32 v88, 16, v84
	v_and_b32_e32 v89, 0xffff0000, v84
	v_pk_fma_f32 v[70:71], v[28:29], v[72:73], v[70:71]
	v_lshlrev_b32_e32 v84, 16, v85
	v_and_b32_e32 v85, 0xffff0000, v85
	ds_read2st64_b32 v[98:99], v83 offset0:140 offset1:144
	v_pk_fma_f32 v[70:71], v[30:31], v[88:89], v[70:71]
	s_waitcnt lgkmcnt(2)
	v_lshlrev_b32_e32 v94, 16, v90
	v_and_b32_e32 v95, 0xffff0000, v90
	v_pk_fma_f32 v[70:71], v[32:33], v[84:85], v[70:71]
	v_lshlrev_b32_e32 v90, 16, v91
	v_and_b32_e32 v91, 0xffff0000, v91
	ds_read_b32 v103, v83 offset:37888
	v_pk_fma_f32 v[70:71], v[34:35], v[94:95], v[70:71]
	s_waitcnt lgkmcnt(2)
	v_lshlrev_b32_e32 v96, 16, v92
	v_and_b32_e32 v97, 0xffff0000, v92
	v_pk_fma_f32 v[70:71], v[36:37], v[90:91], v[70:71]
	v_lshlrev_b32_e32 v92, 16, v93
	v_and_b32_e32 v93, 0xffff0000, v93
	v_pk_fma_f32 v[70:71], v[38:39], v[96:97], v[70:71]
	s_waitcnt lgkmcnt(1)
	v_lshlrev_b32_e32 v100, 16, v98
	v_and_b32_e32 v101, 0xffff0000, v98
	v_pk_fma_f32 v[70:71], v[40:41], v[92:93], v[70:71]
	v_lshlrev_b32_e32 v98, 16, v99
	v_and_b32_e32 v99, 0xffff0000, v99
	v_pk_fma_f32 v[70:71], v[42:43], v[100:101], v[70:71]
	s_waitcnt lgkmcnt(0)
	v_lshlrev_b32_e32 v102, 16, v103
	v_and_b32_e32 v103, 0xffff0000, v103
	v_pk_fma_f32 v[70:71], v[44:45], v[98:99], v[70:71]
	s_nop 0
	v_pk_fma_f32 v[70:71], v[46:47], v[102:103], v[70:71]
	ds_write_b64 v82, v[70:71] offset:14336
	v_pk_mul_f32 v[72:73], v[70:71], v[70:71]
	v_mov_b32_e32 v84, v71
	v_mov_b32_e32 v85, v73
	v_mov_b32_e32 v71, v72
	v_pk_add_f32 v[118:119], v[84:85], v[70:71]
	ds_bpermute_b32 v120, v75, v104
	ds_bpermute_b32 v121, v75, v105
	ds_bpermute_b32 v122, v75, v106
	ds_bpermute_b32 v123, v75, v107
	ds_bpermute_b32 v124, v75, v108
	ds_bpermute_b32 v125, v75, v109
	ds_bpermute_b32 v126, v75, v110
	ds_bpermute_b32 v127, v75, v111
	ds_bpermute_b32 v128, v75, v112
	ds_bpermute_b32 v129, v75, v113
	ds_bpermute_b32 v130, v75, v114
	ds_bpermute_b32 v131, v75, v115
	ds_bpermute_b32 v132, v75, v116
	ds_bpermute_b32 v133, v75, v117
	ds_bpermute_b32 v134, v75, v118
	ds_bpermute_b32 v135, v75, v119
	s_waitcnt lgkmcnt(14)
	v_pk_add_f32 v[104:105], v[104:105], v[120:121]
	s_waitcnt lgkmcnt(12)
	v_pk_add_f32 v[106:107], v[106:107], v[122:123]
	s_waitcnt lgkmcnt(10)
	v_pk_add_f32 v[108:109], v[108:109], v[124:125]
	s_waitcnt lgkmcnt(8)
	v_pk_add_f32 v[110:111], v[110:111], v[126:127]
	s_waitcnt lgkmcnt(6)
	v_pk_add_f32 v[112:113], v[112:113], v[128:129]
	s_waitcnt lgkmcnt(4)
	v_pk_add_f32 v[114:115], v[114:115], v[130:131]
	s_waitcnt lgkmcnt(2)
	v_pk_add_f32 v[116:117], v[116:117], v[132:133]
	s_waitcnt lgkmcnt(0)
	v_pk_add_f32 v[118:119], v[118:119], v[134:135]
	ds_bpermute_b32 v120, v76, v104
	ds_bpermute_b32 v121, v76, v105
	ds_bpermute_b32 v122, v76, v106
	ds_bpermute_b32 v123, v76, v107
	ds_bpermute_b32 v124, v76, v108
	ds_bpermute_b32 v125, v76, v109
	ds_bpermute_b32 v126, v76, v110
	ds_bpermute_b32 v127, v76, v111
	ds_bpermute_b32 v128, v76, v112
	ds_bpermute_b32 v129, v76, v113
	ds_bpermute_b32 v130, v76, v114
	ds_bpermute_b32 v131, v76, v115
	ds_bpermute_b32 v132, v76, v116
	ds_bpermute_b32 v133, v76, v117
	ds_bpermute_b32 v134, v76, v118
	ds_bpermute_b32 v135, v76, v119
	s_waitcnt lgkmcnt(14)
	v_pk_add_f32 v[104:105], v[104:105], v[120:121]
	s_waitcnt lgkmcnt(12)
	v_pk_add_f32 v[106:107], v[106:107], v[122:123]
	s_waitcnt lgkmcnt(10)
	v_pk_add_f32 v[108:109], v[108:109], v[124:125]
	s_waitcnt lgkmcnt(8)
	v_pk_add_f32 v[110:111], v[110:111], v[126:127]
	s_waitcnt lgkmcnt(6)
	v_pk_add_f32 v[112:113], v[112:113], v[128:129]
	s_waitcnt lgkmcnt(4)
	v_pk_add_f32 v[114:115], v[114:115], v[130:131]
	s_waitcnt lgkmcnt(2)
	v_pk_add_f32 v[116:117], v[116:117], v[132:133]
	s_waitcnt lgkmcnt(0)
; DEV float bflo(unsigned u) { return __uint_as_float(u << 16); }
; DEV float bfhi(unsigned u) { return __uint_as_float(u & 0xffff0000u); }
; DEV void conv_tile(const Params& p, int tile, char* smem) {
;     ...
; #pragma unroll 1
;   for (int i = 0; i < 8; i++) {
;     float a0 = bb.x, a1 = bb.y;
; #pragma unroll
;     for (int wi = 0; wi < 31; wi++) {
;       unsigned u = *(const unsigned*)(stg + (i + wi) * 512 + c);
;       a0 += bflo(u) * w0[wi]; a1 += bfhi(u) * w1[wi];
;     }
;     *(float2*)(ybuf + i * 512 + c) = make_float2(a0, a1);
;     float s1 = wave_sum(a0 + a1);
;     float s2 = wave_sum(a0 * a0 + a1 * a1);
;     if (lane == 0) { red[(i * 4 + w) * 2] = s1; red[(i * 4 + w) * 2 + 1] = s2; }
;   }
	v_pk_add_f32 v[118:119], v[118:119], v[134:135]
	ds_bpermute_b32 v120, v77, v104
	ds_bpermute_b32 v121, v77, v105
	ds_bpermute_b32 v122, v77, v106
	ds_bpermute_b32 v123, v77, v107
	ds_bpermute_b32 v124, v77, v108
	ds_bpermute_b32 v125, v77, v109
	ds_bpermute_b32 v126, v77, v110
	ds_bpermute_b32 v127, v77, v111
	ds_bpermute_b32 v128, v77, v112
	ds_bpermute_b32 v129, v77, v113
	ds_bpermute_b32 v130, v77, v114
	ds_bpermute_b32 v131, v77, v115
	ds_bpermute_b32 v132, v77, v116
	ds_bpermute_b32 v133, v77, v117
	ds_bpermute_b32 v134, v77, v118
	ds_bpermute_b32 v135, v77, v119
	s_waitcnt lgkmcnt(14)
	v_pk_add_f32 v[104:105], v[104:105], v[120:121]
	s_waitcnt lgkmcnt(12)
	v_pk_add_f32 v[106:107], v[106:107], v[122:123]
	s_waitcnt lgkmcnt(10)
	v_pk_add_f32 v[108:109], v[108:109], v[124:125]
	s_waitcnt lgkmcnt(8)
	v_pk_add_f32 v[110:111], v[110:111], v[126:127]
	s_waitcnt lgkmcnt(6)
	v_pk_add_f32 v[112:113], v[112:113], v[128:129]
	s_waitcnt lgkmcnt(4)
	v_pk_add_f32 v[114:115], v[114:115], v[130:131]
	s_waitcnt lgkmcnt(2)
	v_pk_add_f32 v[116:117], v[116:117], v[132:133]
	s_waitcnt lgkmcnt(0)
	v_pk_add_f32 v[118:119], v[118:119], v[134:135]
	ds_bpermute_b32 v120, v78, v104
	ds_bpermute_b32 v121, v78, v105
	ds_bpermute_b32 v122, v78, v106
	ds_bpermute_b32 v123, v78, v107
	ds_bpermute_b32 v124, v78, v108
	ds_bpermute_b32 v125, v78, v109
	ds_bpermute_b32 v126, v78, v110
	ds_bpermute_b32 v127, v78, v111
	ds_bpermute_b32 v128, v78, v112
	ds_bpermute_b32 v129, v78, v113
	ds_bpermute_b32 v130, v78, v114
	ds_bpermute_b32 v131, v78, v115
	ds_bpermute_b32 v132, v78, v116
	ds_bpermute_b32 v133, v78, v117
	ds_bpermute_b32 v134, v78, v118
	ds_bpermute_b32 v135, v78, v119
	s_waitcnt lgkmcnt(14)
	v_pk_add_f32 v[104:105], v[104:105], v[120:121]
	s_waitcnt lgkmcnt(12)
	v_pk_add_f32 v[106:107], v[106:107], v[122:123]
	s_waitcnt lgkmcnt(10)
	v_pk_add_f32 v[108:109], v[108:109], v[124:125]
	s_waitcnt lgkmcnt(8)
	v_pk_add_f32 v[110:111], v[110:111], v[126:127]
	s_waitcnt lgkmcnt(6)
	v_pk_add_f32 v[112:113], v[112:113], v[128:129]
	s_waitcnt lgkmcnt(4)
	v_pk_add_f32 v[114:115], v[114:115], v[130:131]
	s_waitcnt lgkmcnt(2)
	v_pk_add_f32 v[116:117], v[116:117], v[132:133]
	s_waitcnt lgkmcnt(0)
	v_pk_add_f32 v[118:119], v[118:119], v[134:135]
	ds_bpermute_b32 v120, v79, v104
	ds_bpermute_b32 v121, v79, v105
	ds_bpermute_b32 v122, v79, v106
	ds_bpermute_b32 v123, v79, v107
	ds_bpermute_b32 v124, v79, v108
	ds_bpermute_b32 v125, v79, v109
	ds_bpermute_b32 v126, v79, v110
	ds_bpermute_b32 v127, v79, v111
	ds_bpermute_b32 v128, v79, v112
	ds_bpermute_b32 v129, v79, v113
	ds_bpermute_b32 v130, v79, v114
	ds_bpermute_b32 v131, v79, v115
	ds_bpermute_b32 v132, v79, v116
	ds_bpermute_b32 v133, v79, v117
	ds_bpermute_b32 v134, v79, v118
	ds_bpermute_b32 v135, v79, v119
	s_waitcnt lgkmcnt(14)
	v_pk_add_f32 v[104:105], v[104:105], v[120:121]
	s_waitcnt lgkmcnt(12)
	v_pk_add_f32 v[106:107], v[106:107], v[122:123]
	s_waitcnt lgkmcnt(10)
	v_pk_add_f32 v[108:109], v[108:109], v[124:125]
	s_waitcnt lgkmcnt(8)
	v_pk_add_f32 v[110:111], v[110:111], v[126:127]
	s_waitcnt lgkmcnt(6)
	v_pk_add_f32 v[112:113], v[112:113], v[128:129]
	s_waitcnt lgkmcnt(4)
	v_pk_add_f32 v[114:115], v[114:115], v[130:131]
	s_waitcnt lgkmcnt(2)
	v_pk_add_f32 v[116:117], v[116:117], v[132:133]
	s_waitcnt lgkmcnt(0)
	v_pk_add_f32 v[118:119], v[118:119], v[134:135]
	ds_bpermute_b32 v120, v80, v104
	ds_bpermute_b32 v121, v80, v105
	ds_bpermute_b32 v122, v80, v106
	ds_bpermute_b32 v123, v80, v107
	ds_bpermute_b32 v124, v80, v108
	ds_bpermute_b32 v125, v80, v109
	ds_bpermute_b32 v126, v80, v110
	ds_bpermute_b32 v127, v80, v111
	ds_bpermute_b32 v128, v80, v112
	ds_bpermute_b32 v129, v80, v113
	ds_bpermute_b32 v130, v80, v114
	ds_bpermute_b32 v131, v80, v115
	ds_bpermute_b32 v132, v80, v116
	ds_bpermute_b32 v133, v80, v117
	ds_bpermute_b32 v134, v80, v118
	ds_bpermute_b32 v135, v80, v119
	s_waitcnt lgkmcnt(14)
	v_pk_add_f32 v[104:105], v[104:105], v[120:121]
	s_waitcnt lgkmcnt(12)
	v_pk_add_f32 v[106:107], v[106:107], v[122:123]
	s_waitcnt lgkmcnt(10)
	v_pk_add_f32 v[108:109], v[108:109], v[124:125]
	s_waitcnt lgkmcnt(8)
	v_pk_add_f32 v[110:111], v[110:111], v[126:127]
	s_waitcnt lgkmcnt(6)
	v_pk_add_f32 v[112:113], v[112:113], v[128:129]
	s_waitcnt lgkmcnt(4)
	v_pk_add_f32 v[114:115], v[114:115], v[130:131]
	s_waitcnt lgkmcnt(2)
	v_pk_add_f32 v[116:117], v[116:117], v[132:133]
	s_waitcnt lgkmcnt(0)
	v_pk_add_f32 v[118:119], v[118:119], v[134:135]
	s_and_saveexec_b64 s[6:7], vcc
	ds_write2_b32 v81, v104, v105 offset0:0 offset1:1
	ds_write2_b32 v81, v106, v107 offset0:8 offset1:9
	ds_write2_b32 v81, v108, v109 offset0:16 offset1:17
	ds_write2_b32 v81, v110, v111 offset0:24 offset1:25
	ds_write2_b32 v81, v112, v113 offset0:32 offset1:33
	ds_write2_b32 v81, v114, v115 offset0:40 offset1:41
	ds_write2_b32 v81, v116, v117 offset0:48 offset1:49
	ds_write2_b32 v81, v118, v119 offset0:56 offset1:57
	s_or_b64 exec, exec, s[6:7]
